# split conversion slices as v49, padded (25 s_nop after the drain) so that the code after the scan phase sits at the same addresses mod 128 as in v46
# baseline (speedup 1.0000x reference)
; __device__ __forceinline__ void rwkv_scan_phase(Frame& F, const bf16* RKV, const float* WAG, const bf16* AGB, const float* k_k, const float* k_a, const float* r_k, bf16* Y, float* BS, float* ST2) {
;     ...
;             ST_FLUSH(NCH - 1);
.Lcsd_dskip:
	s_nop 0
	s_nop 0
	s_nop 0
	s_nop 0
	s_nop 0
	s_nop 0
	s_nop 0
	s_nop 0
	s_nop 0
	s_nop 0
	s_nop 0
	s_nop 0
	s_nop 0
	s_nop 0
	s_nop 0
	s_nop 0
	s_nop 0
	s_nop 0
	s_nop 0
	s_nop 0
	s_nop 0
	s_nop 0
	s_nop 0
	s_nop 0
	s_nop 0
	ds_read_b128 v[0:3], v169
	v_lshl_add_u64 v[4:5], s[44:45], 1, v[106:107]
	s_lshl_b32 s0, s0, 1
	v_lshl_add_u64 v[4:5], v[4:5], 0, s[0:1]
	s_waitcnt lgkmcnt(0)
	v_cvt_pk_bf16_f32 v6, v0, v1
	v_cvt_pk_bf16_f32 v7, v2, v3
	v_lshl_add_u64 v[4:5], v[4:5], 0, v[92:93]
	global_store_dwordx2 v[4:5], v[6:7], off
	v_mul_f32_e32 v5, v0, v0
	v_mul_f32_e32 v7, v1, v1
	v_mul_f32_e32 v9, v2, v2
	v_mul_f32_e32 v11, v3, v3
	v_mov_b32_e32 v4, v0
	v_mov_b32_e32 v6, v1
	v_mov_b32_e32 v8, v2
	v_mov_b32_e32 v10, v3
	v_pk_add_f32 v[0:1], v[4:5], v[6:7]
	v_pk_add_f32 v[2:3], v[8:9], v[10:11]
	s_nop 0
	v_pk_add_f32 v[0:1], v[0:1], v[2:3]
	s_nop 1
	v_mov_b32_dpp v2, v0 quad_perm:[1,0,3,2] row_mask:0xf bank_mask:0xf bound_ctrl:1
	v_mov_b32_dpp v3, v1 quad_perm:[1,0,3,2] row_mask:0xf bank_mask:0xf bound_ctrl:1
	v_pk_add_f32 v[0:1], v[0:1], v[2:3]
	s_nop 1
	v_mov_b32_dpp v2, v0 quad_perm:[2,3,0,1] row_mask:0xf bank_mask:0xf bound_ctrl:1
	v_mov_b32_dpp v3, v1 quad_perm:[2,3,0,1] row_mask:0xf bank_mask:0xf bound_ctrl:1
	v_pk_add_f32 v[0:1], v[0:1], v[2:3]
	s_nop 1
	v_mov_b32_dpp v2, v0 row_half_mirror row_mask:0xf bank_mask:0xf bound_ctrl:1
	v_mov_b32_dpp v3, v1 row_half_mirror row_mask:0xf bank_mask:0xf bound_ctrl:1
	s_and_saveexec_b64 s[6:7], s[4:5]
	s_cbranch_execz .LBB0_1687
	v_lshl_add_u64 v[4:5], s[46:47], 0, v[104:105]
	v_lshlrev_b64 v[4:5], 9, v[4:5]
	v_lshl_add_u64 v[4:5], s[20:21], 0, v[4:5]
	s_lshl_b32 s0, s33, 2
	v_lshl_add_u64 v[4:5], v[4:5], 0, s[0:1]
	s_lshl_b32 s0, s54, 2
	v_lshl_add_u64 v[4:5], v[4:5], 0, s[0:1]
	v_pk_add_f32 v[0:1], v[0:1], v[2:3]
	global_store_dwordx2 v[4:5], v[0:1], off
	s_branch .LBB0_1687
